# attn loop rewritten: hoisted+deeper K/V LDS prefetch, row max of next tile in MFMA shadow, staging in PV section, running-max subtraction folded into QK MFMA C-init
# baseline (speedup 1.0000x reference)
; __device__ __forceinline__ unsigned cvtpk(float lo, float hi) { f32x2_t v = {lo, hi}; bf16x2_t b = __builtin_convertvector(v, bf16x2_t); return __builtin_bit_cast(unsigned, b); }
; __device__ __forceinline__ int crow(int r, int hi) { return (r & 3) + 8 * (r >> 2) + 4 * hi; }
; __device__ __forceinline__ void attn_unit(const Ctx& c, int bh, int qb, const bf16_t* Q, const bf16_t* Kb, const bf16_t* Vb, bf16_t* O) {
;     ...
;     lsum += __int_as_float(__builtin_amdgcn_ds_bpermute((lane ^ 32) * 4, __float_as_int(lsum)));
;     if (hi == 0) wsf[r32] = 1.0f / lsum;
;     asm volatile("" ::: "memory");
;     bf16_t* op = O + (rowbase + q0 + wid * 32) * 1024 + h * 64 + r32;
; #pragma unroll
;     for (int r = 0; r < 16; ++r) { const int qq = crow(r, hi); const float rl = wsf[qq];
;         op[(size_t)qq * 1024] = (bf16_t)(cvtpk(o[0][r] * rl, 0.f) & 0xffffu); op[(size_t)qq * 1024 + 32] = (bf16_t)(cvtpk(o[1][r] * rl, 0.f) & 0xffffu); }
;     asm volatile("" ::: "memory");
.LBB0_276:
	s_or_b64 exec, exec, s[6:7]
	v_or_b32_e32 v160, 0x800, v158
	v_mov_b32_e32 v161, v211
	v_or_b32_e32 v162, 0x1000, v158
	v_mov_b32_e32 v163, v211
	v_or_b32_e32 v164, 0x1800, v158
	v_mov_b32_e32 v165, v211
	v_or_b32_e32 v166, 0x4000, v158
	v_mov_b32_e32 v167, v211
	v_or_b32_e32 v168, 0x4800, v158
	v_mov_b32_e32 v169, v211
	v_or_b32_e32 v170, 0x5000, v158
	v_mov_b32_e32 v171, v211
	v_or_b32_e32 v172, 0x5800, v158
	v_mov_b32_e32 v173, v211
	v_or_b32_e32 v174, 0x8000, v158
	v_mov_b32_e32 v175, v211
	v_or_b32_e32 v176, 0x8800, v158
	v_mov_b32_e32 v177, v211
	v_or_b32_e32 v178, 0x9000, v158
	v_mov_b32_e32 v179, v211
	v_or_b32_e32 v180, 0x9800, v158
	v_mov_b32_e32 v181, v211
	v_or_b32_e32 v182, 0xc000, v158
	v_mov_b32_e32 v183, v211
	v_or_b32_e32 v184, 0xc800, v158
	v_mov_b32_e32 v185, v211
	v_or_b32_e32 v186, 0xd000, v158
	v_mov_b32_e32 v187, v211
	v_or_b32_e32 v188, 0xd800, v158
	v_mov_b32_e32 v189, v211
	s_lshl_b64 s[6:7], s[46:47], 11
	s_waitcnt lgkmcnt(0)
	ds_read_b128 v[32:35], v221
	ds_read_b128 v[36:39], v221 offset:32
	s_add_u32 s5, s76, s6
	s_addc_u32 s6, s77, s7
	s_lshl_b32 s4, s4, 1
	s_add_u32 s4, s5, s4
	s_addc_u32 s5, s6, 0
	v_mov_b32_e32 v193, v211
	v_lshl_add_u64 v[40:41], s[4:5], 0, v[192:193]
	s_waitcnt lgkmcnt(1)
	v_mul_f32_e32 v0, v0, v32
	v_mul_f32_e32 v16, v16, v32
	v_lshl_add_u64 v[42:43], v[40:41], 0, v[158:159]
	v_cvt_pk_bf16_f32 v0, v0, s0
	v_cvt_pk_bf16_f32 v16, v16, s0
	global_store_short v[42:43], v0, off offset:64
	v_mul_f32_e32 v0, v17, v33
	global_store_short v[42:43], v16, off
	v_cvt_pk_bf16_f32 v0, v0, s0
	v_lshl_add_u64 v[16:17], v[40:41], 0, v[160:161]
	global_store_short v[16:17], v0, off
	v_mul_f32_e32 v0, v1, v33
	v_cvt_pk_bf16_f32 v0, v0, s0
	global_store_short v[16:17], v0, off offset:64
	v_mul_f32_e32 v0, v18, v34
	v_mul_f32_e32 v2, v2, v34
	v_cvt_pk_bf16_f32 v16, v0, s0
	v_lshl_add_u64 v[0:1], v[40:41], 0, v[162:163]
	v_cvt_pk_bf16_f32 v2, v2, s0
	global_store_short v[0:1], v16, off
	global_store_short v[0:1], v2, off offset:64
	v_mul_f32_e32 v0, v19, v35
	v_cvt_pk_bf16_f32 v2, v0, s0
	v_lshl_add_u64 v[0:1], v[40:41], 0, v[164:165]
	global_store_short v[0:1], v2, off
	v_mul_f32_e32 v2, v3, v35
	v_cvt_pk_bf16_f32 v2, v2, s0
	global_store_short v[0:1], v2, off offset:64
	s_waitcnt lgkmcnt(0)
	v_mul_f32_e32 v0, v20, v36
	v_cvt_pk_bf16_f32 v2, v0, s0
	v_lshl_add_u64 v[0:1], v[40:41], 0, v[166:167]
	global_store_short v[0:1], v2, off
	v_mul_f32_e32 v2, v4, v36
	v_cvt_pk_bf16_f32 v2, v2, s0
	global_store_short v[0:1], v2, off offset:64
	v_mul_f32_e32 v0, v21, v37
	v_cvt_pk_bf16_f32 v2, v0, s0
	v_lshl_add_u64 v[0:1], v[40:41], 0, v[168:169]
	global_store_short v[0:1], v2, off
	v_mul_f32_e32 v2, v5, v37
	v_cvt_pk_bf16_f32 v2, v2, s0
	global_store_short v[0:1], v2, off offset:64
	v_mul_f32_e32 v0, v22, v38
	v_cvt_pk_bf16_f32 v2, v0, s0
	v_lshl_add_u64 v[0:1], v[40:41], 0, v[170:171]
	global_store_short v[0:1], v2, off
	v_mul_f32_e32 v2, v6, v38
	v_cvt_pk_bf16_f32 v2, v2, s0
	global_store_short v[0:1], v2, off offset:64
	v_mul_f32_e32 v0, v23, v39
	v_cvt_pk_bf16_f32 v0, v0, s0
	v_lshl_add_u64 v[4:5], v[40:41], 0, v[172:173]
	global_store_short v[4:5], v0, off
	ds_read_b128 v[0:3], v221 offset:64
	v_mul_f32_e32 v6, v7, v39
	v_cvt_pk_bf16_f32 v6, v6, s0
	global_store_short v[4:5], v6, off offset:64
	ds_read_b128 v[4:7], v221 offset:96
	s_waitcnt lgkmcnt(1)
	v_mul_f32_e32 v16, v24, v0
	v_mul_f32_e32 v0, v8, v0
	v_cvt_pk_bf16_f32 v18, v16, s0
	v_lshl_add_u64 v[16:17], v[40:41], 0, v[174:175]
	v_cvt_pk_bf16_f32 v0, v0, s0
	global_store_short v[16:17], v0, off offset:64
	v_mul_f32_e32 v0, v25, v1
	global_store_short v[16:17], v18, off
	v_cvt_pk_bf16_f32 v0, v0, s0
	v_lshl_add_u64 v[16:17], v[40:41], 0, v[176:177]
	global_store_short v[16:17], v0, off
	v_mul_f32_e32 v0, v9, v1
	v_cvt_pk_bf16_f32 v0, v0, s0
	global_store_short v[16:17], v0, off offset:64
	v_mul_f32_e32 v0, v26, v2
	v_mul_f32_e32 v2, v10, v2
	v_cvt_pk_bf16_f32 v8, v0, s0
	v_lshl_add_u64 v[0:1], v[40:41], 0, v[178:179]
	v_cvt_pk_bf16_f32 v2, v2, s0
	global_store_short v[0:1], v8, off
	global_store_short v[0:1], v2, off offset:64
	v_mul_f32_e32 v0, v27, v3
	v_cvt_pk_bf16_f32 v2, v0, s0
	v_lshl_add_u64 v[0:1], v[40:41], 0, v[180:181]
	global_store_short v[0:1], v2, off
	v_mul_f32_e32 v2, v11, v3
	v_cvt_pk_bf16_f32 v2, v2, s0
	global_store_short v[0:1], v2, off offset:64
	s_waitcnt lgkmcnt(0)
	v_mul_f32_e32 v0, v28, v4
	v_cvt_pk_bf16_f32 v2, v0, s0
	v_lshl_add_u64 v[0:1], v[40:41], 0, v[182:183]
	global_store_short v[0:1], v2, off
	v_mul_f32_e32 v2, v12, v4
	v_cvt_pk_bf16_f32 v2, v2, s0
	global_store_short v[0:1], v2, off offset:64
	v_mul_f32_e32 v0, v29, v5
	v_cvt_pk_bf16_f32 v2, v0, s0
	v_lshl_add_u64 v[0:1], v[40:41], 0, v[184:185]
	global_store_short v[0:1], v2, off
	v_mul_f32_e32 v2, v13, v5
	v_cvt_pk_bf16_f32 v2, v2, s0
	global_store_short v[0:1], v2, off offset:64
	v_mul_f32_e32 v0, v30, v6
	v_cvt_pk_bf16_f32 v2, v0, s0
	v_lshl_add_u64 v[0:1], v[40:41], 0, v[186:187]
	global_store_short v[0:1], v2, off
	v_mul_f32_e32 v2, v14, v6
	v_cvt_pk_bf16_f32 v2, v2, s0
	global_store_short v[0:1], v2, off offset:64
	v_mul_f32_e32 v0, v31, v7
	v_cvt_pk_bf16_f32 v2, v0, s0
	v_lshl_add_u64 v[0:1], v[40:41], 0, v[188:189]
	global_store_short v[0:1], v2, off
	v_mul_f32_e32 v2, v15, v7
	v_cvt_pk_bf16_f32 v2, v2, s0
	global_store_short v[0:1], v2, off offset:64
	s_add_i32 s3, s3, s15
	s_cmpk_gt_i32 s3, 0x3ff
	s_cbranch_scc1 .LBB0_314

; #define AT_LOAD(t_, S) do { const int tc_ = (t_) < NT ? (t_) : NT - 1; const size_t off_ = (size_t)tc_ * 64; k0r##S = *(const u32x4*)(kg0 + off_ * 768); k1r##S = *(const u32x4*)(kg1 + off_ * 768); vr##S = *(const u32x4*)(vg + off_ * 512); } while (0)
; #define AT_STORE(bo_, S) do { unsigned char* lb_ = lds + (bo_); *(u32x4*)(lb_ + ks0) = k0r##S; if (tid < 256) *(u32x4*)(lb_ + ks1) = k1r##S; *(u32x4*)(lb_ + vs0) = vr##S; } while (0)
; __device__ __forceinline__ void attn_unit(const Ctx& c, int bh, int qb, const bf16_t* Q, const bf16_t* Kb, const bf16_t* Vb, bf16_t* O) {
;     ...
;     AT_LOAD(0, A); AT_LOAD(1, B); AT_STORE(b0, A); AT_LOAD(2, A); AT_STORE(b1, B); AT_LOAD(3, B);
;     __syncthreads();
;     f32x16 pA0, pA1, pB0, pB1;
;     AT_QK(pA0, pA1, b0);
;     for (int t = 0; t < NT; t += 2) {
.LBB0_289:
	s_or_b64 exec, exec, s[6:7]
	s_waitcnt vmcnt(3)
	ds_write_b128 v16, v[0:3] offset:36864
	v_add_co_u32_e32 v0, vcc, 0x48000, v194
	s_mov_b32 s56, 0
	s_nop 0
	v_addc_co_u32_e32 v1, vcc, 0, v195, vcc
	global_load_dwordx4 v[134:137], v[0:1], off
	v_add_co_u32_e32 v0, vcc, 0x48000, v196
	s_mov_b32 s57, s56
	s_nop 0
	v_addc_co_u32_e32 v1, vcc, 0, v197, vcc
	global_load_dwordx4 v[138:141], v[0:1], off
	v_add_co_u32_e32 v0, vcc, 0x30000, v198
	s_mov_b32 s58, s56
	s_nop 0
	v_addc_co_u32_e32 v1, vcc, 0, v199, vcc
	global_load_dwordx4 v[142:145], v[0:1], off
	v_add_u32_e32 v0, v203, v204
	s_waitcnt lgkmcnt(0)
	s_barrier
	ds_read_b128 v[16:19], v0 offset:512
	ds_read_b128 v[20:23], v0
	s_waitcnt lgkmcnt(0)
	v_mfma_f32_32x32x16_bf16 v[32:47], v[20:23], v[98:101], 0
	v_add_u32_e32 v20, v203, v205
	s_mov_b32 s59, s56
	s_mov_b32 s60, s56
	s_mov_b32 s61, s56
	s_mov_b32 s62, s56
	s_mov_b32 s63, s56
	s_mov_b32 s64, s56
	v_mfma_f32_32x32x16_bf16 v[48:63], v[16:19], v[98:101], 0
	ds_read_b128 v[16:19], v20 offset:2560
	ds_read_b128 v[20:23], v20 offset:2048
	s_mov_b32 s65, s56
	s_mov_b32 s66, s56
	s_mov_b32 s67, s56
	s_mov_b32 s68, s56
	s_mov_b32 s69, s56
	s_mov_b32 s70, s56
	s_waitcnt lgkmcnt(0)
	v_mfma_f32_32x32x16_bf16 v[32:47], v[20:23], v[102:105], v[32:47]
	v_add_u32_e32 v20, v203, v206
	s_mov_b32 s71, s56
	v_mov_b64_e32 v[0:1], s[56:57]
	v_mov_b64_e32 v[14:15], s[70:71]
	s_lshl_b32 s5, s5, 2
	v_readlane_b32 s6, v254, 63
	v_mov_b64_e32 v[2:3], s[58:59]
	v_mfma_f32_32x32x16_bf16 v[48:63], v[16:19], v[102:105], v[48:63]
	ds_read_b128 v[16:19], v20 offset:4608
	ds_read_b128 v[20:23], v20 offset:4096
	v_mov_b64_e32 v[4:5], s[60:61]
	v_mov_b64_e32 v[6:7], s[62:63]
	v_mov_b64_e32 v[8:9], s[64:65]
	v_mov_b64_e32 v[10:11], s[66:67]
	v_mov_b64_e32 v[12:13], s[68:69]
	s_mov_b32 s47, s17
	s_waitcnt lgkmcnt(0)
	v_mfma_f32_32x32x16_bf16 v[32:47], v[20:23], v[106:109], v[32:47]
	v_add_u32_e32 v20, v203, v207
	s_lshl_b32 s4, s4, 6
	s_add_i32 s8, s5, 4
	s_add_i32 s9, s5, s6
	s_or_b32 s10, s5, 3
	v_mov_b32_e32 v191, 0
	v_mov_b32_e32 v174, 0
	v_mov_b32_e32 v175, 0
	v_mov_b32_e32 v176, 0
	v_mov_b32_e32 v177, 0
	v_mov_b32_e32 v178, 0
	v_mov_b32_e32 v179, 0
	v_mov_b32_e32 v180, 0
	v_mov_b32_e32 v181, 0
	v_mov_b32_e32 v182, 0
	v_mov_b32_e32 v183, 0
	v_mov_b32_e32 v184, 0
	v_mov_b32_e32 v185, 0
	v_mov_b32_e32 v186, 0
	v_mov_b32_e32 v187, 0
	v_mov_b32_e32 v188, 0
	v_mov_b32_e32 v189, 0
	v_mfma_f32_32x32x16_bf16 v[48:63], v[16:19], v[106:109], v[48:63]
	ds_read_b128 v[16:19], v20 offset:6656
	ds_read_b128 v[20:23], v20 offset:6144
	s_mov_b32 s12, 0xc000
	s_movk_i32 s11, 0x6000
	s_mov_b32 s13, s56
	s_waitcnt lgkmcnt(0)
	v_mfma_f32_32x32x16_bf16 v[32:47], v[20:23], v[110:113], v[32:47]
	v_add_u32_e32 v20, v203, v208
	v_mfma_f32_32x32x16_bf16 v[48:63], v[16:19], v[110:113], v[48:63]
	ds_read_b128 v[16:19], v20 offset:8704
	ds_read_b128 v[20:23], v20 offset:8192
	s_waitcnt lgkmcnt(0)
	v_mfma_f32_32x32x16_bf16 v[32:47], v[20:23], v[114:117], v[32:47]
	v_add_u32_e32 v20, v203, v209
	v_mfma_f32_32x32x16_bf16 v[48:63], v[16:19], v[114:117], v[48:63]
	ds_read_b128 v[16:19], v20 offset:10752
	ds_read_b128 v[20:23], v20 offset:10240
	s_waitcnt lgkmcnt(0)
	v_mfma_f32_32x32x16_bf16 v[32:47], v[20:23], v[118:121], v[32:47]
	v_mfma_f32_32x32x16_bf16 v[48:63], v[16:19], v[118:121], v[48:63]
	v_mov_b64_e32 v[30:31], v[14:15]
	v_mov_b64_e32 v[28:29], v[12:13]
	v_mov_b64_e32 v[26:27], v[10:11]
	v_mov_b64_e32 v[24:25], v[8:9]
	v_mov_b64_e32 v[22:23], v[6:7]
	v_mov_b64_e32 v[20:21], v[4:5]
	v_mov_b64_e32 v[18:19], v[2:3]
	v_mov_b64_e32 v[16:17], v[0:1]
	s_nop 15
	v_max3_f32 v232, v32, v33, v34
	v_max3_f32 v233, v35, v36, v37
	v_max3_f32 v232, v232, v38, v39
	v_max3_f32 v233, v233, v40, v41
	v_max3_f32 v232, v232, v42, v43
	v_max3_f32 v233, v233, v44, v45
	v_max3_f32 v232, v232, v46, v47
	v_max3_f32 v233, v233, v48, v49
	v_max3_f32 v232, v232, v50, v51
	v_max3_f32 v233, v233, v52, v53
	v_max3_f32 v232, v232, v54, v55
	v_max3_f32 v233, v233, v56, v57
	v_max3_f32 v232, v232, v58, v59
	v_max3_f32 v233, v233, v60, v61
	v_max3_f32 v232, v232, v62, v63
	v_max3_f32 v232, v232, v233, v233
.LBB0_290:
	s_add_i32 s27, s12, 0
	s_mov_b32 s25, s11
	s_mov_b32 s11, s56
	v_add_u32_e32 v213, s25, v203
	v_add_u32_e32 v214, v213, v204
	ds_read_b128 v[160:163], v214
	ds_read_b128 v[164:167], v214 offset:512
	v_add_u32_e32 v214, v213, v205
	ds_read_b128 v[224:227], v214 offset:2048
	ds_read_b128 v[228:231], v214 offset:2560
	v_add_u32_e32 v214, v213, v206
	ds_read_b128 v[242:245], v214 offset:4096
	ds_read_b128 v[246:249], v214 offset:4608
	s_cmp_gt_u32 s13, s9
	s_cbranch_scc1 .Lat_skip1
	v_mov_b32_e32 v233, v232
	s_cmp_eq_u32 s13, 0
	s_cselect_b64 s[6:7], -1, 0
	v_permlane32_swap_b32_e32 v232, v233
	v_max3_f32 v232, v232, v233, v232
	v_cmp_lt_f32_e32 vcc, 0x41000000, v232
	s_or_b64 vcc, s[6:7], vcc
	s_cbranch_vccz .LBB0_299
	s_nop 0
	v_cndmask_b32_e32 v233, 0, v232, vcc
	v_exp_f32_e64 v64, -v233
	s_and_saveexec_b64 s[6:7], s[44:45]
	ds_write_b32 v220, v64
	s_or_b64 exec, exec, s[6:7]
	v_mul_f32_e32 v191, v191, v64
	ds_read_b128 v[64:67], v221
	ds_read_b128 v[68:71], v221 offset:32
	ds_read_b128 v[72:75], v221 offset:64
	ds_read_b128 v[76:79], v221 offset:96
	s_waitcnt lgkmcnt(3)
	v_pk_mul_f32 v[18:19], v[18:19], v[66:67]
	s_waitcnt lgkmcnt(2)
	v_pk_mul_f32 v[22:23], v[22:23], v[70:71]
	s_waitcnt lgkmcnt(1)
	v_pk_mul_f32 v[26:27], v[26:27], v[74:75]
	s_waitcnt lgkmcnt(0)
	v_pk_mul_f32 v[30:31], v[30:31], v[78:79]
	v_pk_mul_f32 v[28:29], v[28:29], v[76:77]
	v_pk_mul_f32 v[24:25], v[24:25], v[72:73]
	v_pk_mul_f32 v[20:21], v[20:21], v[68:69]
	v_pk_mul_f32 v[16:17], v[16:17], v[64:65]
	v_pk_mul_f32 v[14:15], v[14:15], v[78:79]
	v_pk_mul_f32 v[10:11], v[10:11], v[74:75]
	v_pk_mul_f32 v[6:7], v[6:7], v[70:71]
	v_pk_mul_f32 v[2:3], v[2:3], v[66:67]
	v_pk_mul_f32 v[12:13], v[12:13], v[76:77]
	v_pk_mul_f32 v[8:9], v[8:9], v[72:73]
	v_pk_mul_f32 v[4:5], v[4:5], v[68:69]
	v_pk_mul_f32 v[0:1], v[0:1], v[64:65]
	v_sub_f32_e32 v32, v32, v233
	v_sub_f32_e32 v33, v33, v233
	v_sub_f32_e32 v34, v34, v233
	v_sub_f32_e32 v35, v35, v233
	v_sub_f32_e32 v36, v36, v233
	v_sub_f32_e32 v37, v37, v233
	v_sub_f32_e32 v38, v38, v233
	v_sub_f32_e32 v39, v39, v233
	v_sub_f32_e32 v40, v40, v233
	v_sub_f32_e32 v41, v41, v233
	v_sub_f32_e32 v42, v42, v233
	v_sub_f32_e32 v43, v43, v233
	v_sub_f32_e32 v44, v44, v233
	v_sub_f32_e32 v45, v45, v233
	v_sub_f32_e32 v46, v46, v233
	v_sub_f32_e32 v47, v47, v233
	v_sub_f32_e32 v48, v48, v233
	v_sub_f32_e32 v49, v49, v233
	v_sub_f32_e32 v50, v50, v233
	v_sub_f32_e32 v51, v51, v233
	v_sub_f32_e32 v52, v52, v233
	v_sub_f32_e32 v53, v53, v233
	v_sub_f32_e32 v54, v54, v233
	v_sub_f32_e32 v55, v55, v233
	v_sub_f32_e32 v56, v56, v233
	v_sub_f32_e32 v57, v57, v233
	v_sub_f32_e32 v58, v58, v233
	v_sub_f32_e32 v59, v59, v233
	v_sub_f32_e32 v60, v60, v233
	v_sub_f32_e32 v61, v61, v233
	v_sub_f32_e32 v62, v62, v233
	v_sub_f32_e32 v63, v63, v233
	v_sub_f32_e32 v174, v174, v233
	v_sub_f32_e32 v175, v175, v233
	v_sub_f32_e32 v176, v176, v233
	v_sub_f32_e32 v177, v177, v233
	v_sub_f32_e32 v178, v178, v233
	v_sub_f32_e32 v179, v179, v233
	v_sub_f32_e32 v180, v180, v233
	v_sub_f32_e32 v181, v181, v233
	v_sub_f32_e32 v182, v182, v233
	v_sub_f32_e32 v183, v183, v233
	v_sub_f32_e32 v184, v184, v233
	v_sub_f32_e32 v185, v185, v233
	v_sub_f32_e32 v186, v186, v233
	v_sub_f32_e32 v187, v187, v233
	v_sub_f32_e32 v188, v188, v233
	v_sub_f32_e32 v189, v189, v233
.LBB0_299:
	v_add_u32_e32 v193, s25, v203
	s_waitcnt lgkmcnt(5)
	v_mfma_f32_32x32x16_bf16 v[64:79], v[160:163], v[98:101], v[174:189]
	v_exp_f32_e32 v32, v32
	v_exp_f32_e32 v33, v33
	s_waitcnt lgkmcnt(4)
	v_mfma_f32_32x32x16_bf16 v[80:95], v[164:167], v[98:101], v[174:189]
	v_add_u32_e32 v214, v193, v207
	ds_read_b128 v[160:163], v214 offset:6144
	ds_read_b128 v[164:167], v214 offset:6656
	v_exp_f32_e32 v34, v34
	v_exp_f32_e32 v35, v35
	s_waitcnt lgkmcnt(5)
	v_mfma_f32_32x32x16_bf16 v[64:79], v[224:227], v[102:105], v[64:79]
	v_exp_f32_e32 v36, v36
	v_exp_f32_e32 v37, v37
	s_waitcnt lgkmcnt(4)
	v_mfma_f32_32x32x16_bf16 v[80:95], v[228:231], v[102:105], v[80:95]
	v_add_u32_e32 v214, v193, v209
	ds_read_b128 v[224:227], v214 offset:10240
	ds_read_b128 v[228:231], v214 offset:10752
	v_exp_f32_e32 v38, v38
	v_exp_f32_e32 v39, v39
	s_waitcnt lgkmcnt(5)
	v_mfma_f32_32x32x16_bf16 v[64:79], v[242:245], v[106:109], v[64:79]
	v_exp_f32_e32 v40, v40
	v_exp_f32_e32 v41, v41
	s_waitcnt lgkmcnt(4)
	v_mfma_f32_32x32x16_bf16 v[80:95], v[246:249], v[106:109], v[80:95]
	v_add_u32_e32 v214, v193, v208
	ds_read_b128 v[242:245], v214 offset:8192
	ds_read_b128 v[246:249], v214 offset:8704
	v_add_u32_e32 v213, s11, v218
	v_exp_f32_e32 v42, v42
	v_exp_f32_e32 v43, v43
	s_waitcnt lgkmcnt(5)
	v_mfma_f32_32x32x16_bf16 v[64:79], v[160:163], v[110:113], v[64:79]
	v_exp_f32_e32 v44, v44
	v_exp_f32_e32 v45, v45
	s_waitcnt lgkmcnt(4)
	v_mfma_f32_32x32x16_bf16 v[80:95], v[164:167], v[110:113], v[80:95]
	ds_read_b64_tr_b16 v[168:169], v213 offset:12288
	ds_read_b64_tr_b16 v[170:171], v213 offset:13824
	v_exp_f32_e32 v46, v46
	v_exp_f32_e32 v47, v47
	s_waitcnt lgkmcnt(3)
	v_mfma_f32_32x32x16_bf16 v[64:79], v[242:245], v[114:117], v[64:79]
	ds_read_b64_tr_b16 v[250:251], v213 offset:12352
	ds_read_b64_tr_b16 v[252:253], v213 offset:13888
	v_cvt_pk_bf16_f32 v242, v32, v33
	v_cvt_pk_bf16_f32 v243, v34, v35
	v_exp_f32_e32 v48, v48
	v_exp_f32_e32 v49, v49
	s_waitcnt lgkmcnt(4)
	v_mfma_f32_32x32x16_bf16 v[80:95], v[246:249], v[114:117], v[80:95]
	ds_read_b64_tr_b16 v[160:161], v213 offset:15360
	ds_read_b64_tr_b16 v[162:163], v213 offset:16896
	v_cvt_pk_bf16_f32 v244, v36, v37
	v_cvt_pk_bf16_f32 v245, v38, v39
	v_exp_f32_e32 v50, v50
	v_exp_f32_e32 v51, v51
	s_waitcnt lgkmcnt(9)
	v_mfma_f32_32x32x16_bf16 v[64:79], v[224:227], v[118:121], v[64:79]
	ds_read_b64_tr_b16 v[164:165], v213 offset:15424
	ds_read_b64_tr_b16 v[166:167], v213 offset:16960
	v_cvt_pk_bf16_f32 v224, v40, v41
	v_cvt_pk_bf16_f32 v225, v42, v43
	v_exp_f32_e32 v52, v52
	v_exp_f32_e32 v53, v53
	s_waitcnt lgkmcnt(10)
	v_mfma_f32_32x32x16_bf16 v[80:95], v[228:231], v[118:121], v[80:95]
	ds_read_b64_tr_b16 v[228:229], v213 offset:18432
	ds_read_b64_tr_b16 v[230:231], v213 offset:19968
	v_cvt_pk_bf16_f32 v226, v44, v45
	v_cvt_pk_bf16_f32 v227, v46, v47
	v_exp_f32_e32 v54, v54
	v_exp_f32_e32 v55, v55
	s_waitcnt lgkmcnt(8)
	v_mfma_f32_32x32x16_bf16 v[16:31], v[242:245], v[168:171], v[16:31]
	ds_read_b64_tr_b16 v[168:169], v213 offset:18496
	ds_read_b64_tr_b16 v[170:171], v213 offset:20032
	v_cvt_pk_bf16_f32 v246, v48, v49
	v_exp_f32_e32 v56, v56
	v_exp_f32_e32 v57, v57
	v_add_f32_e32 v216, v32, v34
	v_add_f32_e32 v217, v33, v35
	s_waitcnt lgkmcnt(8)
	v_mfma_f32_32x32x16_bf16 v[0:15], v[242:245], v[250:253], v[0:15]
	ds_read_b64_tr_b16 v[250:251], v213 offset:21504
	ds_read_b64_tr_b16 v[252:253], v213 offset:23040
	v_cvt_pk_bf16_f32 v247, v50, v51
	v_exp_f32_e32 v58, v58
	v_exp_f32_e32 v59, v59
	v_add_f32_e32 v216, v216, v36
	v_add_f32_e32 v217, v217, v37
	s_waitcnt lgkmcnt(8)
	v_mfma_f32_32x32x16_bf16 v[16:31], v[224:227], v[160:163], v[16:31]
	ds_read_b64_tr_b16 v[160:161], v213 offset:21568
	ds_read_b64_tr_b16 v[162:163], v213 offset:23104
	v_cvt_pk_bf16_f32 v248, v52, v53
	v_exp_f32_e32 v60, v60
	v_exp_f32_e32 v61, v61
	v_add_f32_e32 v216, v216, v38
	v_add_f32_e32 v217, v217, v39
	v_add_u32_e32 v215, s27, v97
	s_waitcnt vmcnt(5)
	ds_write_b128 v215, v[122:125]
	s_cmp_eq_u64 s[42:43], 0
	s_cbranch_scc1 .Lat_w1_1_body
	v_add_u32_e32 v215, s27, v147
	s_waitcnt vmcnt(4)
	ds_write_b128 v215, v[126:129]
.Lat_w1_1_body:
	v_max3_f32 v232, v64, v65, v66
	v_max3_f32 v233, v67, v68, v69
	s_waitcnt lgkmcnt(9)
	v_mfma_f32_32x32x16_bf16 v[0:15], v[224:227], v[164:167], v[0:15]
	v_cvt_pk_bf16_f32 v249, v54, v55
	v_exp_f32_e32 v62, v62
	v_exp_f32_e32 v63, v63
	v_add_f32_e32 v216, v216, v40
	v_add_f32_e32 v217, v217, v41
	v_add_u32_e32 v215, s27, v200
	s_waitcnt vmcnt(3)
	ds_write_b128 v215, v[130:133] offset:12288
	v_max3_f32 v232, v232, v70, v71
	v_max3_f32 v233, v233, v72, v73
	s_waitcnt lgkmcnt(8)
	v_mfma_f32_32x32x16_bf16 v[16:31], v[246:249], v[228:231], v[16:31]
	v_cvt_pk_bf16_f32 v242, v56, v57
	v_cvt_pk_bf16_f32 v243, v58, v59
	v_add_f32_e32 v216, v216, v42
	v_add_f32_e32 v217, v217, v43
	v_add_f32_e32 v216, v216, v44
	v_add_f32_e32 v217, v217, v45
	v_add_f32_e32 v216, v216, v46
	v_add_f32_e32 v217, v217, v47
	s_add_i32 s6, s13, 4
	s_cmp_lt_u32 s13, s5
	s_cselect_b32 s16, s6, s10
	v_mad_u64_u32 v[122:123], s[6:7], s16, v239, v[194:195]
	v_mad_u64_u32 v[126:127], s[6:7], s16, v239, v[196:197]
	s_lshl_b64 s[6:7], s[16:17], 16
	s_nop 0
	v_lshl_add_u64 v[130:131], v[198:199], 0, s[6:7]
	global_load_dwordx4 v[122:125], v[122:123], off
	s_nop 0
	global_load_dwordx4 v[126:129], v[126:127], off
	s_nop 0
	global_load_dwordx4 v[130:133], v[130:131], off
	v_max3_f32 v232, v232, v74, v75
	v_max3_f32 v233, v233, v76, v77
	v_max3_f32 v232, v232, v78, v79
	s_waitcnt lgkmcnt(6)
	v_mfma_f32_32x32x16_bf16 v[0:15], v[246:249], v[168:171], v[0:15]
	v_cvt_pk_bf16_f32 v244, v60, v61
	v_cvt_pk_bf16_f32 v245, v62, v63
	v_add_f32_e32 v216, v216, v48
	v_add_f32_e32 v217, v217, v49
	v_add_f32_e32 v216, v216, v50
	v_add_f32_e32 v217, v217, v51
	v_add_f32_e32 v216, v216, v52
	v_add_f32_e32 v217, v217, v53
	v_max3_f32 v233, v233, v80, v81
	v_max3_f32 v232, v232, v82, v83
	v_max3_f32 v233, v233, v84, v85
	s_waitcnt lgkmcnt(4)
	v_mfma_f32_32x32x16_bf16 v[16:31], v[242:245], v[250:253], v[16:31]
	v_add_f32_e32 v216, v216, v54
	v_add_f32_e32 v217, v217, v55
	v_add_f32_e32 v216, v216, v56
	v_add_f32_e32 v217, v217, v57
	v_add_f32_e32 v216, v216, v58
	v_add_f32_e32 v217, v217, v59
	v_max3_f32 v232, v232, v86, v87
	v_max3_f32 v233, v233, v88, v89
	v_max3_f32 v232, v232, v90, v91
	s_waitcnt lgkmcnt(2)
	v_mfma_f32_32x32x16_bf16 v[0:15], v[242:245], v[160:163], v[0:15]
	v_add_f32_e32 v216, v216, v60
	v_add_f32_e32 v217, v217, v61
	v_add_f32_e32 v216, v216, v62
	v_add_f32_e32 v217, v217, v63
	v_add_f32_e32 v216, v216, v217
	v_add_f32_e32 v191, v191, v216
	v_max3_f32 v233, v233, v92, v93
	v_max3_f32 v232, v232, v94, v95
	v_max3_f32 v232, v232, v233, v233
	s_branch .LBB0_300
.Lat_skip1:
	v_add_u32_e32 v215, s27, v97
	s_waitcnt vmcnt(5)
	ds_write_b128 v215, v[122:125]
	s_cmp_eq_u64 s[42:43], 0
	s_cbranch_scc1 .Lat_w1_1_skip
	v_add_u32_e32 v215, s27, v147
	s_waitcnt vmcnt(4)
	ds_write_b128 v215, v[126:129]
.Lat_w1_1_skip:
	v_add_u32_e32 v215, s27, v200
	s_waitcnt vmcnt(3)
	ds_write_b128 v215, v[130:133] offset:12288
	s_add_i32 s6, s13, 4
	s_cmp_lt_u32 s13, s5
	s_cselect_b32 s16, s6, s10
	v_mad_u64_u32 v[122:123], s[6:7], s16, v239, v[194:195]
	v_mad_u64_u32 v[126:127], s[6:7], s16, v239, v[196:197]
	s_lshl_b64 s[6:7], s[16:17], 16
	s_nop 0
	v_lshl_add_u64 v[130:131], v[198:199], 0, s[6:7]
	global_load_dwordx4 v[122:125], v[122:123], off
	s_nop 0
	global_load_dwordx4 v[126:129], v[126:127], off
	s_nop 0
	global_load_dwordx4 v[130:133], v[130:131], off
.LBB0_300:
	s_waitcnt lgkmcnt(0)
	s_barrier
	v_add3_u32 v213, s27, v201, v202
	v_add_u32_e32 v214, v213, v204
	ds_read_b128 v[160:163], v214
	ds_read_b128 v[164:167], v214 offset:512
	v_add_u32_e32 v214, v213, v205
	ds_read_b128 v[224:227], v214 offset:2048
	ds_read_b128 v[228:231], v214 offset:2560
	v_add_u32_e32 v214, v213, v206
	ds_read_b128 v[242:245], v214 offset:4096
	ds_read_b128 v[246:249], v214 offset:4608
	s_cmp_ge_u32 s13, s9
	s_cbranch_scc1 .Lat_skip2
	v_mov_b32_e32 v233, v232
	s_nop 1
	v_permlane32_swap_b32_e32 v232, v233
	v_max3_f32 v232, v232, v233, v232
	v_cmp_lt_f32_e32 vcc, 0x41000000, v232
	s_cbranch_vccz .LBB0_309
	s_nop 0
	v_cndmask_b32_e32 v233, 0, v232, vcc
	v_exp_f32_e64 v32, -v233
	s_and_saveexec_b64 s[6:7], s[44:45]
	ds_write_b32 v220, v32
	s_or_b64 exec, exec, s[6:7]
	v_mul_f32_e32 v191, v191, v32
	ds_read_b128 v[32:35], v221
	ds_read_b128 v[36:39], v221 offset:32
	ds_read_b128 v[40:43], v221 offset:64
	ds_read_b128 v[44:47], v221 offset:96
	s_waitcnt lgkmcnt(3)
	v_pk_mul_f32 v[18:19], v[18:19], v[34:35]
	s_waitcnt lgkmcnt(2)
	v_pk_mul_f32 v[22:23], v[22:23], v[38:39]
	s_waitcnt lgkmcnt(1)
	v_pk_mul_f32 v[26:27], v[26:27], v[42:43]
	s_waitcnt lgkmcnt(0)
	v_pk_mul_f32 v[30:31], v[30:31], v[46:47]
	v_pk_mul_f32 v[28:29], v[28:29], v[44:45]
	v_pk_mul_f32 v[24:25], v[24:25], v[40:41]
	v_pk_mul_f32 v[20:21], v[20:21], v[36:37]
	v_pk_mul_f32 v[16:17], v[16:17], v[32:33]
	v_pk_mul_f32 v[14:15], v[14:15], v[46:47]
	v_pk_mul_f32 v[10:11], v[10:11], v[42:43]
	v_pk_mul_f32 v[6:7], v[6:7], v[38:39]
	v_pk_mul_f32 v[2:3], v[2:3], v[34:35]
	v_pk_mul_f32 v[12:13], v[12:13], v[44:45]
	v_pk_mul_f32 v[8:9], v[8:9], v[40:41]
	v_pk_mul_f32 v[4:5], v[4:5], v[36:37]
	v_pk_mul_f32 v[0:1], v[0:1], v[32:33]
	v_sub_f32_e32 v64, v64, v233
	v_sub_f32_e32 v65, v65, v233
	v_sub_f32_e32 v66, v66, v233
	v_sub_f32_e32 v67, v67, v233
	v_sub_f32_e32 v68, v68, v233
	v_sub_f32_e32 v69, v69, v233
	v_sub_f32_e32 v70, v70, v233
	v_sub_f32_e32 v71, v71, v233
	v_sub_f32_e32 v72, v72, v233
	v_sub_f32_e32 v73, v73, v233
	v_sub_f32_e32 v74, v74, v233
	v_sub_f32_e32 v75, v75, v233
	v_sub_f32_e32 v76, v76, v233
	v_sub_f32_e32 v77, v77, v233
	v_sub_f32_e32 v78, v78, v233
	v_sub_f32_e32 v79, v79, v233
	v_sub_f32_e32 v80, v80, v233
	v_sub_f32_e32 v81, v81, v233
	v_sub_f32_e32 v82, v82, v233
	v_sub_f32_e32 v83, v83, v233
	v_sub_f32_e32 v84, v84, v233
	v_sub_f32_e32 v85, v85, v233
	v_sub_f32_e32 v86, v86, v233
	v_sub_f32_e32 v87, v87, v233
	v_sub_f32_e32 v88, v88, v233
	v_sub_f32_e32 v89, v89, v233
	v_sub_f32_e32 v90, v90, v233
	v_sub_f32_e32 v91, v91, v233
	v_sub_f32_e32 v92, v92, v233
	v_sub_f32_e32 v93, v93, v233
	v_sub_f32_e32 v94, v94, v233
	v_sub_f32_e32 v95, v95, v233
	v_sub_f32_e32 v174, v174, v233
	v_sub_f32_e32 v175, v175, v233
	v_sub_f32_e32 v176, v176, v233
	v_sub_f32_e32 v177, v177, v233
	v_sub_f32_e32 v178, v178, v233
	v_sub_f32_e32 v179, v179, v233
	v_sub_f32_e32 v180, v180, v233
	v_sub_f32_e32 v181, v181, v233
	v_sub_f32_e32 v182, v182, v233
	v_sub_f32_e32 v183, v183, v233
	v_sub_f32_e32 v184, v184, v233
	v_sub_f32_e32 v185, v185, v233
	v_sub_f32_e32 v186, v186, v233
	v_sub_f32_e32 v187, v187, v233
	v_sub_f32_e32 v188, v188, v233
	v_sub_f32_e32 v189, v189, v233
.LBB0_309:
	v_add3_u32 v212, s27, v201, v202
	s_waitcnt lgkmcnt(5)
	v_mfma_f32_32x32x16_bf16 v[32:47], v[160:163], v[98:101], v[174:189]
	v_exp_f32_e32 v64, v64
	v_exp_f32_e32 v65, v65
	s_waitcnt lgkmcnt(4)
	v_mfma_f32_32x32x16_bf16 v[48:63], v[164:167], v[98:101], v[174:189]
	v_add_u32_e32 v214, v212, v207
	ds_read_b128 v[160:163], v214 offset:6144
	ds_read_b128 v[164:167], v214 offset:6656
	v_exp_f32_e32 v66, v66
	v_exp_f32_e32 v67, v67
	s_waitcnt lgkmcnt(5)
	v_mfma_f32_32x32x16_bf16 v[32:47], v[224:227], v[102:105], v[32:47]
	v_exp_f32_e32 v68, v68
	v_exp_f32_e32 v69, v69
	s_waitcnt lgkmcnt(4)
	v_mfma_f32_32x32x16_bf16 v[48:63], v[228:231], v[102:105], v[48:63]
	v_add_u32_e32 v214, v212, v209
	ds_read_b128 v[224:227], v214 offset:10240
	ds_read_b128 v[228:231], v214 offset:10752
	v_exp_f32_e32 v70, v70
	v_exp_f32_e32 v71, v71
	s_waitcnt lgkmcnt(5)
	v_mfma_f32_32x32x16_bf16 v[32:47], v[242:245], v[106:109], v[32:47]
	v_exp_f32_e32 v72, v72
	v_exp_f32_e32 v73, v73
	s_waitcnt lgkmcnt(4)
	v_mfma_f32_32x32x16_bf16 v[48:63], v[246:249], v[106:109], v[48:63]
	v_add_u32_e32 v214, v212, v208
	ds_read_b128 v[242:245], v214 offset:8192
	ds_read_b128 v[246:249], v214 offset:8704
	v_add_u32_e32 v213, s25, v218
	v_exp_f32_e32 v74, v74
	v_exp_f32_e32 v75, v75
	s_waitcnt lgkmcnt(5)
	v_mfma_f32_32x32x16_bf16 v[32:47], v[160:163], v[110:113], v[32:47]
	v_exp_f32_e32 v76, v76
	v_exp_f32_e32 v77, v77
	s_waitcnt lgkmcnt(4)
	v_mfma_f32_32x32x16_bf16 v[48:63], v[164:167], v[110:113], v[48:63]
	ds_read_b64_tr_b16 v[168:169], v213 offset:12288
	ds_read_b64_tr_b16 v[170:171], v213 offset:13824
	v_exp_f32_e32 v78, v78
	v_exp_f32_e32 v79, v79
	s_waitcnt lgkmcnt(3)
	v_mfma_f32_32x32x16_bf16 v[32:47], v[242:245], v[114:117], v[32:47]
	ds_read_b64_tr_b16 v[250:251], v213 offset:12352
	ds_read_b64_tr_b16 v[252:253], v213 offset:13888
	v_cvt_pk_bf16_f32 v242, v64, v65
	v_cvt_pk_bf16_f32 v243, v66, v67
	v_exp_f32_e32 v80, v80
	v_exp_f32_e32 v81, v81
	s_waitcnt lgkmcnt(4)
	v_mfma_f32_32x32x16_bf16 v[48:63], v[246:249], v[114:117], v[48:63]
	ds_read_b64_tr_b16 v[160:161], v213 offset:15360
	ds_read_b64_tr_b16 v[162:163], v213 offset:16896
	v_cvt_pk_bf16_f32 v244, v68, v69
	v_cvt_pk_bf16_f32 v245, v70, v71
	v_exp_f32_e32 v82, v82
	v_exp_f32_e32 v83, v83
	s_waitcnt lgkmcnt(9)
	v_mfma_f32_32x32x16_bf16 v[32:47], v[224:227], v[118:121], v[32:47]
	ds_read_b64_tr_b16 v[164:165], v213 offset:15424
	ds_read_b64_tr_b16 v[166:167], v213 offset:16960
	v_cvt_pk_bf16_f32 v224, v72, v73
	v_cvt_pk_bf16_f32 v225, v74, v75
	v_exp_f32_e32 v84, v84
	v_exp_f32_e32 v85, v85
	s_waitcnt lgkmcnt(10)
	v_mfma_f32_32x32x16_bf16 v[48:63], v[228:231], v[118:121], v[48:63]
	ds_read_b64_tr_b16 v[228:229], v213 offset:18432
	ds_read_b64_tr_b16 v[230:231], v213 offset:19968
	v_cvt_pk_bf16_f32 v226, v76, v77
	v_cvt_pk_bf16_f32 v227, v78, v79
	v_exp_f32_e32 v86, v86
	v_exp_f32_e32 v87, v87
	s_waitcnt lgkmcnt(8)
	v_mfma_f32_32x32x16_bf16 v[16:31], v[242:245], v[168:171], v[16:31]
	ds_read_b64_tr_b16 v[168:169], v213 offset:18496
	ds_read_b64_tr_b16 v[170:171], v213 offset:20032
	v_cvt_pk_bf16_f32 v246, v80, v81
	v_exp_f32_e32 v88, v88
	v_exp_f32_e32 v89, v89
	v_add_f32_e32 v216, v64, v66
	v_add_f32_e32 v217, v65, v67
	s_waitcnt lgkmcnt(8)
	v_mfma_f32_32x32x16_bf16 v[0:15], v[242:245], v[250:253], v[0:15]
	ds_read_b64_tr_b16 v[250:251], v213 offset:21504
	ds_read_b64_tr_b16 v[252:253], v213 offset:23040
	v_cvt_pk_bf16_f32 v247, v82, v83
	v_exp_f32_e32 v90, v90
	v_exp_f32_e32 v91, v91
	v_add_f32_e32 v216, v216, v68
	v_add_f32_e32 v217, v217, v69
	s_waitcnt lgkmcnt(8)
	v_mfma_f32_32x32x16_bf16 v[16:31], v[224:227], v[160:163], v[16:31]
	ds_read_b64_tr_b16 v[160:161], v213 offset:21568
	ds_read_b64_tr_b16 v[162:163], v213 offset:23104
	v_cvt_pk_bf16_f32 v248, v84, v85
	v_exp_f32_e32 v92, v92
	v_exp_f32_e32 v93, v93
	v_add_f32_e32 v216, v216, v70
	v_add_f32_e32 v217, v217, v71
	v_add_u32_e32 v215, s11, v97
	s_waitcnt vmcnt(5)
	ds_write_b128 v215, v[134:137]
	s_cmp_eq_u64 s[42:43], 0
	s_cbranch_scc1 .Lat_w1_2_body
	v_add_u32_e32 v215, s11, v147
	s_waitcnt vmcnt(4)
	ds_write_b128 v215, v[138:141]
.Lat_w1_2_body:
	v_max3_f32 v232, v32, v33, v34
	v_max3_f32 v233, v35, v36, v37
	s_waitcnt lgkmcnt(9)
	v_mfma_f32_32x32x16_bf16 v[0:15], v[224:227], v[164:167], v[0:15]
	v_cvt_pk_bf16_f32 v249, v86, v87
	v_exp_f32_e32 v94, v94
	v_exp_f32_e32 v95, v95
	v_add_f32_e32 v216, v216, v72
	v_add_f32_e32 v217, v217, v73
	v_add_u32_e32 v215, s11, v200
	s_waitcnt vmcnt(3)
	ds_write_b128 v215, v[142:145] offset:12288
	v_max3_f32 v232, v232, v38, v39
	v_max3_f32 v233, v233, v40, v41
	s_waitcnt lgkmcnt(8)
	v_mfma_f32_32x32x16_bf16 v[16:31], v[246:249], v[228:231], v[16:31]
	v_cvt_pk_bf16_f32 v242, v88, v89
	v_cvt_pk_bf16_f32 v243, v90, v91
	v_add_f32_e32 v216, v216, v74
	v_add_f32_e32 v217, v217, v75
	v_add_f32_e32 v216, v216, v76
	v_add_f32_e32 v217, v217, v77
	v_add_f32_e32 v216, v216, v78
	v_add_f32_e32 v217, v217, v79
	s_add_i32 s6, s13, 5
	s_cmp_lt_u32 s6, s8
	s_cselect_b32 s16, s6, s10
	v_mad_u64_u32 v[134:135], s[6:7], s16, v239, v[194:195]
	v_mad_u64_u32 v[138:139], s[6:7], s16, v239, v[196:197]
	s_lshl_b64 s[6:7], s[16:17], 16
	s_nop 0
	v_lshl_add_u64 v[142:143], v[198:199], 0, s[6:7]
	global_load_dwordx4 v[134:137], v[134:135], off
	s_nop 0
	global_load_dwordx4 v[138:141], v[138:139], off
	s_nop 0
	global_load_dwordx4 v[142:145], v[142:143], off
	v_max3_f32 v232, v232, v42, v43
	v_max3_f32 v233, v233, v44, v45
	v_max3_f32 v232, v232, v46, v47
	s_waitcnt lgkmcnt(6)
	v_mfma_f32_32x32x16_bf16 v[0:15], v[246:249], v[168:171], v[0:15]
	v_cvt_pk_bf16_f32 v244, v92, v93
	v_cvt_pk_bf16_f32 v245, v94, v95
	v_add_f32_e32 v216, v216, v80
	v_add_f32_e32 v217, v217, v81
	v_add_f32_e32 v216, v216, v82
	v_add_f32_e32 v217, v217, v83
	v_add_f32_e32 v216, v216, v84
	v_add_f32_e32 v217, v217, v85
	v_max3_f32 v233, v233, v48, v49
	v_max3_f32 v232, v232, v50, v51
	v_max3_f32 v233, v233, v52, v53
	s_waitcnt lgkmcnt(4)
	v_mfma_f32_32x32x16_bf16 v[16:31], v[242:245], v[250:253], v[16:31]
	v_add_f32_e32 v216, v216, v86
	v_add_f32_e32 v217, v217, v87
	v_add_f32_e32 v216, v216, v88
	v_add_f32_e32 v217, v217, v89
	v_add_f32_e32 v216, v216, v90
	v_add_f32_e32 v217, v217, v91
	v_max3_f32 v232, v232, v54, v55
	v_max3_f32 v233, v233, v56, v57
	v_max3_f32 v232, v232, v58, v59
	s_waitcnt lgkmcnt(2)
	v_mfma_f32_32x32x16_bf16 v[0:15], v[242:245], v[160:163], v[0:15]
	v_add_f32_e32 v216, v216, v92
	v_add_f32_e32 v217, v217, v93
	v_add_f32_e32 v216, v216, v94
	v_add_f32_e32 v217, v217, v95
	v_add_f32_e32 v216, v216, v217
	v_add_f32_e32 v191, v191, v216
	v_max3_f32 v233, v233, v60, v61
	v_max3_f32 v232, v232, v62, v63
	v_max3_f32 v232, v232, v233, v233
	s_branch .LBB0_310
.Lat_skip2:
	v_add_u32_e32 v215, s11, v97
	s_waitcnt vmcnt(5)
	ds_write_b128 v215, v[134:137]
	s_cmp_eq_u64 s[42:43], 0
	s_cbranch_scc1 .Lat_w1_2_skip
	v_add_u32_e32 v215, s11, v147
	s_waitcnt vmcnt(4)
	ds_write_b128 v215, v[138:141]
.Lat_w1_2_skip:
	v_add_u32_e32 v215, s11, v200
	s_waitcnt vmcnt(3)
	ds_write_b128 v215, v[142:145] offset:12288
	s_add_i32 s6, s13, 5
	s_cmp_lt_u32 s6, s8
	s_cselect_b32 s16, s6, s10
	v_mad_u64_u32 v[134:135], s[6:7], s16, v239, v[194:195]
	v_mad_u64_u32 v[138:139], s[6:7], s16, v239, v[196:197]
	s_lshl_b64 s[6:7], s[16:17], 16
	s_nop 0
	v_lshl_add_u64 v[142:143], v[198:199], 0, s[6:7]
	global_load_dwordx4 v[134:137], v[134:135], off
	s_nop 0
	global_load_dwordx4 v[138:141], v[138:139], off
	s_nop 0
	global_load_dwordx4 v[142:145], v[142:143], off
